# ATTN unit-end barrier: no store drain (LDS-only wait) before the next unit
# speedup vs baseline: 1.0020x; 1.0020x over previous
.LBB0_321:
	v_lshlrev_b64 v[64:65], 11, v[156:157]
	v_lshl_add_u64 v[64:65], s[14:15], 0, v[64:65]
	s_mov_b32 s19, s27
	v_lshl_add_u64 v[64:65], v[64:65], 0, s[18:19]
	v_mov_b32_e32 v155, v169
	v_lshl_add_u64 v[64:65], v[64:65], 0, v[154:155]
	v_cvt_pk_bf16_f32 v48, v48, v49
	v_cvt_pk_bf16_f32 v49, v50, v51
	v_cvt_pk_bf16_f32 v32, v32, v33
	v_cvt_pk_bf16_f32 v33, v34, v35
	v_cvt_pk_bf16_f32 v16, v16, v17
	v_cvt_pk_bf16_f32 v17, v18, v19
	v_cvt_pk_bf16_f32 v0, v0, v1
	v_cvt_pk_bf16_f32 v1, v2, v3
	global_store_dwordx2 v[64:65], v[48:49], off
	v_cvt_pk_bf16_f32 v48, v52, v53
	v_cvt_pk_bf16_f32 v49, v54, v55
	global_store_dwordx2 v[64:65], v[32:33], off offset:64
	v_cvt_pk_bf16_f32 v32, v36, v37
	v_cvt_pk_bf16_f32 v33, v38, v39
	global_store_dwordx2 v[64:65], v[16:17], off offset:128
	v_cvt_pk_bf16_f32 v16, v20, v21
	v_cvt_pk_bf16_f32 v17, v22, v23
	global_store_dwordx2 v[64:65], v[0:1], off offset:192
	v_cvt_pk_bf16_f32 v0, v4, v5
	v_cvt_pk_bf16_f32 v1, v6, v7
	global_store_dwordx2 v[64:65], v[48:49], off offset:16
	v_cvt_pk_bf16_f32 v48, v56, v57
	v_cvt_pk_bf16_f32 v49, v58, v59
	global_store_dwordx2 v[64:65], v[32:33], off offset:80
	v_cvt_pk_bf16_f32 v32, v40, v41
	v_cvt_pk_bf16_f32 v33, v42, v43
	global_store_dwordx2 v[64:65], v[16:17], off offset:144
	v_cvt_pk_bf16_f32 v16, v24, v25
	v_cvt_pk_bf16_f32 v17, v26, v27
	global_store_dwordx2 v[64:65], v[0:1], off offset:208
	v_cvt_pk_bf16_f32 v0, v8, v9
	v_cvt_pk_bf16_f32 v1, v10, v11
	global_store_dwordx2 v[64:65], v[48:49], off offset:32
	v_cvt_pk_bf16_f32 v48, v60, v61
	v_cvt_pk_bf16_f32 v49, v62, v63
	global_store_dwordx2 v[64:65], v[32:33], off offset:96
	v_cvt_pk_bf16_f32 v32, v44, v45
	v_cvt_pk_bf16_f32 v33, v46, v47
	global_store_dwordx2 v[64:65], v[16:17], off offset:160
	v_cvt_pk_bf16_f32 v16, v28, v29
	v_cvt_pk_bf16_f32 v17, v30, v31
	global_store_dwordx2 v[64:65], v[0:1], off offset:224
	v_cvt_pk_bf16_f32 v0, v12, v13
	v_cvt_pk_bf16_f32 v1, v14, v15
	global_store_dwordx2 v[64:65], v[48:49], off offset:48
	global_store_dwordx2 v[64:65], v[32:33], off offset:112
	global_store_dwordx2 v[64:65], v[16:17], off offset:176
	global_store_dwordx2 v[64:65], v[0:1], off offset:240
	s_waitcnt lgkmcnt(0)
	s_barrier
	s_add_i32 s22, s22, s24
	s_add_i32 s29, s29, s24
	s_cmpk_lt_i32 s22, 0x200
	s_cbranch_scc0 .LBB0_337
